# P65: layer-0 down-projection epilogue - the eight conditional modulation-vector loads issued together (one wait instead of a 4-step load/wait ladder)
# speedup vs baseline: 1.0031x; 1.0031x over previous
.LBB0_1446:
	v_lshl_add_u32 v192, s65, 8, v202
	v_add_u32_e32 v66, 0xffff8000, v192
	v_cndmask_b32_e64 v66, v192, v66, s[6:7]
	v_lshl_add_u32 v176, s36, 8, v204
	v_ashrrev_i32_e32 v67, 31, v66
	v_ashrrev_i32_e32 v177, 31, v176
	v_lshlrev_b64 v[66:67], 11, v[66:67]
	v_lshl_add_u64 v[154:155], v[176:177], 1, v[66:67]
	v_lshl_add_u64 v[198:199], s[40:41], 0, v[154:155]
	s_mov_b32 s6, 0x8000
	v_add_co_u32_e32 v66, vcc, s6, v198
	s_lshl_b64 s[6:7], s[38:39], 2
	s_nop 0
	v_addc_co_u32_e32 v67, vcc, 0, v199, vcc
	s_add_u32 s38, s54, s6
	global_load_dwordx4 v[146:149], v[198:199], off
	global_load_dwordx4 v[162:165], v[198:199], off offset:256
	global_load_dwordx4 v[150:153], v[66:67], off offset:256
	global_load_dwordx4 v[158:161], v[66:67], off
	s_addc_u32 s39, s55, s7
	v_lshlrev_b64 v[66:67], 2, v[176:177]
	v_lshl_add_u64 v[74:75], s[38:39], 0, v[66:67]
	global_load_dwordx4 v[70:73], v[74:75], off
	s_add_u32 s6, s56, s6
	s_addc_u32 s7, s57, s7
	v_lshl_add_u64 v[156:157], s[22:23], 0, v[66:67]
	v_lshl_add_u64 v[196:197], s[6:7], 0, v[66:67]
	v_cndmask_b32_e64 v66, 0, 1, s[82:83]
	v_mov_b32_e32 v184, 0
	v_cmp_ne_u32_e64 s[6:7], 1, v66
	s_andn2_b64 vcc, exec, s[82:83]
	v_mov_b32_e32 v186, 0
	v_mov_b32_e32 v187, 0
	v_mov_b32_e32 v188, 0
	v_mov_b32_e32 v189, 0
	s_cbranch_vccnz .LBB0_1448
	global_load_dwordx4 v[66:69], v[196:197], off
	global_load_dwordx4 v[76:79], v[156:157], off
	global_load_dwordx4 v[214:217], v[196:197], off offset:16
	global_load_dwordx4 v[218:221], v[156:157], off offset:16
	global_load_dwordx4 v[222:225], v[196:197], off offset:512
	global_load_dwordx4 v[226:229], v[156:157], off offset:512
	global_load_dwordx4 v[230:233], v[196:197], off offset:528
	global_load_dwordx4 v[234:237], v[156:157], off offset:528
	s_waitcnt vmcnt(0)
	v_pk_add_f32 v[68:69], v[68:69], 1.0 op_sel_hi:[1,0]
	v_pk_add_f32 v[66:67], v[66:67], 1.0 op_sel_hi:[1,0]
	v_pk_mul_f32 v[188:189], v[78:79], v[68:69]
	v_pk_mul_f32 v[186:187], v[76:77], v[66:67]
.LBB0_1448:
	global_load_dwordx4 v[78:81], v[74:75], off offset:16
	s_and_b64 vcc, exec, s[6:7]
	v_mov_b32_e32 v185, 0
	v_mov_b32_e32 v194, 0
	v_mov_b32_e32 v195, 0
	s_movk_i32 s71, 0x5800
	s_movk_i32 s70, 0x2c00
	s_cbranch_vccnz .LBB0_1450
	v_pk_add_f32 v[216:217], v[216:217], 1.0 op_sel_hi:[1,0]
	v_pk_add_f32 v[214:215], v[214:215], 1.0 op_sel_hi:[1,0]
	v_pk_mul_f32 v[194:195], v[220:221], v[216:217]
	v_pk_mul_f32 v[184:185], v[218:219], v[214:215]
.LBB0_1450:
	global_load_dwordx4 v[66:69], v[74:75], off offset:512
	v_mov_b32_e32 v178, 0
	s_and_b64 vcc, exec, s[6:7]
	v_mov_b32_e32 v180, 0
	v_mov_b32_e32 v181, 0
	v_mov_b32_e32 v182, 0
	v_mov_b32_e32 v183, 0
	s_cbranch_vccnz .LBB0_1452
	v_pk_add_f32 v[76:77], v[224:225], 1.0 op_sel_hi:[1,0]
	v_pk_add_f32 v[222:223], v[222:223], 1.0 op_sel_hi:[1,0]
	v_pk_mul_f32 v[182:183], v[228:229], v[76:77]
	v_pk_mul_f32 v[180:181], v[226:227], v[222:223]
.LBB0_1452:
	global_load_dwordx4 v[74:77], v[74:75], off offset:528
	s_and_b64 vcc, exec, s[6:7]
	v_mov_b32_e32 v179, 0
	v_mov_b32_e32 v190, 0
	v_mov_b32_e32 v191, 0
	s_cbranch_vccnz .LBB0_1454
	v_pk_add_f32 v[156:157], v[232:233], 1.0 op_sel_hi:[1,0]
	v_pk_add_f32 v[178:179], v[230:231], 1.0 op_sel_hi:[1,0]
	v_pk_mul_f32 v[190:191], v[236:237], v[156:157]
	v_pk_mul_f32 v[178:179], v[234:235], v[178:179]
